# M3 unit tail: norm-gain loads hoisted above the last barrier, second store no longer waited
# baseline (speedup 1.0000x reference)
.LBB0_704:
	s_or_b64 exec, exec, s[0:1]
	v_lshl_add_u32 v71, v89, 7, s54
	s_waitcnt lgkmcnt(0)
	s_barrier
	ds_read_b128 v[94:97], v71
	ds_read_b128 v[98:101], v71 offset:16
	v_lshlrev_b32_e32 v88, 2, v88
	v_add_u32_e32 v47, s54, v47
	s_add_u32 s0, s36, s58
	v_readlane_b32 s56, v246, 4
	s_waitcnt lgkmcnt(0)
	v_pk_add_f32 v[90:91], v[96:97], v[100:101]
	v_pk_add_f32 v[94:95], v[94:95], v[98:99]
	s_addc_u32 s1, s37, 0
	v_pk_mov_b32 v[96:97], v[94:95], v[90:91] op_sel:[1,0]
	v_mov_b32_e32 v95, v91
	v_pk_add_f32 v[90:91], v[96:97], v[94:95]
	v_readlane_b32 s68, v246, 16
	v_add_f32_e32 v71, v90, v91
	v_fmamk_f32 v71, v71, 0x3c000000, v151
	v_mul_f32_e32 v75, 0x4b800000, v71
	v_cmp_gt_f32_e32 vcc, s55, v71
	v_readlane_b32 s69, v246, 17
	s_add_u32 s2, s68, s4
	v_cndmask_b32_e32 v71, v71, v75, vcc
	v_rsq_f32_e32 v71, v71
	v_and_b32_e32 v75, 0xffffffc0, v157
	v_add3_u32 v75, 0, v75, v88
	s_addc_u32 s3, s69, 0
	v_mul_f32_e32 v88, 0x45800000, v71
	v_cndmask_b32_e32 v71, v71, v88, vcc
	v_mul_f32_e32 v56, v56, v71
	v_mad_u32_u24 v71, v89, s91, v75
	ds_write_b32 v71, v56 offset:53248
	v_lshl_add_u32 v56, v3, 5, s54
	ds_read_b128 v[88:91], v56
	ds_read_b128 v[94:97], v56 offset:16
	v_mad_u32_u24 v3, v3, s95, v75
	s_waitcnt vmcnt(1)
	v_lshlrev_b32_e32 v75, 16, v67
	s_waitcnt vmcnt(0)
	v_lshlrev_b32_e32 v208, 2, v156
	global_load_dwordx4 v[200:203], v208, s[2:3]
	global_load_dwordx4 v[204:207], v208, s[2:3] offset:16
	v_and_b32_e32 v108, 0xffff0000, v60
	v_lshlrev_b32_e32 v109, 16, v61
	s_waitcnt lgkmcnt(0)
	v_pk_add_f32 v[90:91], v[90:91], v[96:97]
	v_pk_add_f32 v[88:89], v[88:89], v[94:95]
	v_and_b32_e32 v113, 0xffff0000, v61
	v_pk_mov_b32 v[94:95], v[88:89], v[90:91] op_sel:[1,0]
	v_mov_b32_e32 v89, v91
	v_pk_add_f32 v[88:89], v[94:95], v[88:89]
	v_lshlrev_b32_e32 v114, 16, v62
	v_add_f32_e32 v56, v88, v89
	v_fmamk_f32 v56, v56, 0x3c000000, v151
	v_mul_f32_e32 v71, 0x4b800000, v56
	v_cmp_gt_f32_e32 vcc, s55, v56
	v_and_b32_e32 v62, 0xffff0000, v62
	v_mov_b64_e32 v[106:107], v[22:23]
	v_cndmask_b32_e32 v56, v56, v71, vcc
	v_rsq_f32_e32 v56, v56
	v_mov_b64_e32 v[102:103], v[18:19]
	v_lshlrev_b32_e32 v115, 16, v63
	v_and_b32_e32 v63, 0xffff0000, v63
	v_mul_f32_e32 v71, 0x45800000, v56
	v_cndmask_b32_e32 v56, v56, v71, vcc
	v_mul_f32_e32 v56, v59, v56
	ds_write_b32 v3, v56 offset:53248
	v_lshl_add_u32 v56, v57, 5, s54
	ds_read_b128 v[88:91], v56
	ds_read_b128 v[94:97], v56 offset:16
	v_lshl_add_u32 v71, v87, 5, s54
	v_lshl_add_u64 v[144:145], v[144:145], 0, s[16:17]
	v_mov_b32_e32 v112, v154
	v_mov_b32_e32 v111, v129
	s_waitcnt lgkmcnt(0)
	v_pk_add_f32 v[56:57], v[90:91], v[96:97]
	v_pk_add_f32 v[88:89], v[88:89], v[94:95]
	v_mov_b64_e32 v[98:99], v[14:15]
	v_pk_mov_b32 v[90:91], v[88:89], v[56:57] op_sel:[1,0]
	v_mov_b32_e32 v89, v57
	v_pk_add_f32 v[56:57], v[90:91], v[88:89]
	v_mov_b64_e32 v[104:105], v[20:21]
	v_add_f32_e32 v56, v56, v57
	v_fmamk_f32 v56, v56, 0x3c000000, v151
	v_mul_f32_e32 v57, 0x4b800000, v56
	v_cmp_gt_f32_e32 vcc, s55, v56
	v_mov_b64_e32 v[100:101], v[16:17]
	v_mov_b64_e32 v[96:97], v[12:13]
	v_cndmask_b32_e32 v56, v56, v57, vcc
	v_rsq_f32_e32 v56, v56
	v_mov_b32_e32 v110, v1
	s_add_i32 s38, s38, s39
	s_add_i32 s40, s40, s41
	v_mul_f32_e32 v57, 0x45800000, v56
	v_cndmask_b32_e32 v56, v56, v57, vcc
	v_mul_f32_e32 v56, v58, v56
	ds_write_b32 v3, v56 offset:53776
	ds_read_b128 v[56:59], v71
	ds_read_b128 v[88:91], v71 offset:16
	v_lshl_add_u32 v71, v92, 5, s54
	v_mov_b32_e32 v158, v155
	v_readlane_b32 s57, v246, 5
	v_readlane_b32 s58, v246, 6
	s_waitcnt lgkmcnt(0)
	v_pk_add_f32 v[58:59], v[58:59], v[90:91]
	v_pk_add_f32 v[56:57], v[56:57], v[88:89]
	v_readlane_b32 s59, v246, 7
	v_pk_mov_b32 v[88:89], v[56:57], v[58:59] op_sel:[1,0]
	v_mov_b32_e32 v57, v59
	v_pk_add_f32 v[56:57], v[88:89], v[56:57]
	v_readlane_b32 s60, v246, 8
	v_add_f32_e32 v56, v56, v57
	v_fmamk_f32 v56, v56, 0x3c000000, v151
	v_mul_f32_e32 v57, 0x4b800000, v56
	v_cmp_gt_f32_e32 vcc, s55, v56
	v_readlane_b32 s61, v246, 9
	v_readlane_b32 s62, v246, 10
	v_cndmask_b32_e32 v56, v56, v57, vcc
	v_rsq_f32_e32 v56, v56
	v_readlane_b32 s63, v246, 11
	v_readlane_b32 s64, v246, 12
	v_readlane_b32 s65, v246, 13
	v_mul_f32_e32 v57, 0x45800000, v56
	v_cndmask_b32_e32 v56, v56, v57, vcc
	v_mul_f32_e32 v56, v83, v56
	ds_write_b32 v3, v56 offset:54304
	ds_read_b128 v[56:59], v71
	ds_read_b128 v[88:91], v71 offset:16
	v_lshl_add_u32 v71, v93, 5, s54
	v_mov_b32_e32 v83, v0
	v_mov_b64_e32 v[94:95], v[10:11]
	v_mov_b64_e32 v[92:93], v[8:9]
	s_waitcnt lgkmcnt(0)
	v_pk_add_f32 v[58:59], v[58:59], v[90:91]
	v_pk_add_f32 v[56:57], v[56:57], v[88:89]
	v_readlane_b32 s66, v246, 14
	v_pk_mov_b32 v[88:89], v[56:57], v[58:59] op_sel:[1,0]
	v_mov_b32_e32 v57, v59
	v_pk_add_f32 v[56:57], v[88:89], v[56:57]
	v_readlane_b32 s67, v246, 15
	v_add_f32_e32 v56, v56, v57
	v_fmamk_f32 v56, v56, 0x3c000000, v151
	v_mul_f32_e32 v57, 0x4b800000, v56
	v_cmp_gt_f32_e32 vcc, s55, v56
	v_readlane_b32 s70, v246, 18
	v_readlane_b32 s71, v246, 19
	v_cndmask_b32_e32 v56, v56, v57, vcc
	v_rsq_f32_e32 v56, v56
	s_nop 0
	v_mul_f32_e32 v57, 0x45800000, v56
	v_cndmask_b32_e32 v56, v56, v57, vcc
	v_mul_f32_e32 v52, v52, v56
	ds_write_b32 v3, v52 offset:61168
	ds_read_b128 v[56:59], v71
	ds_read_b128 v[88:91], v71 offset:16
	v_lshl_add_u32 v71, v76, 5, s54
	s_waitcnt lgkmcnt(0)
	v_pk_add_f32 v[58:59], v[58:59], v[90:91]
	v_pk_add_f32 v[56:57], v[56:57], v[88:89]
	s_nop 0
	v_pk_mov_b32 v[88:89], v[56:57], v[58:59] op_sel:[1,0]
	v_mov_b32_e32 v57, v59
	v_pk_add_f32 v[56:57], v[88:89], v[56:57]
	s_nop 0
	v_add_f32_e32 v52, v56, v57
	v_fmamk_f32 v52, v52, 0x3c000000, v151
	v_mul_f32_e32 v56, 0x4b800000, v52
	v_cmp_gt_f32_e32 vcc, s55, v52
	s_nop 1
	v_cndmask_b32_e32 v52, v52, v56, vcc
	v_rsq_f32_e32 v52, v52
	s_nop 0
	v_mul_f32_e32 v56, 0x45800000, v52
	v_cndmask_b32_e32 v52, v52, v56, vcc
	v_mul_f32_e32 v52, v77, v52
	ds_write_b32 v3, v52 offset:61696
	ds_read_b128 v[56:59], v71
	ds_read_b128 v[88:91], v71 offset:16
	v_lshl_add_u32 v71, v78, 5, s54
	s_waitcnt lgkmcnt(0)
	v_pk_add_f32 v[58:59], v[58:59], v[90:91]
	v_pk_add_f32 v[56:57], v[56:57], v[88:89]
	s_nop 0
	v_pk_mov_b32 v[76:77], v[56:57], v[58:59] op_sel:[1,0]
	v_mov_b32_e32 v57, v59
	v_pk_add_f32 v[56:57], v[76:77], v[56:57]
	v_and_b32_e32 v76, 0xffff0000, v67
	v_add_f32_e32 v52, v56, v57
	v_fmamk_f32 v52, v52, 0x3c000000, v151
	v_mul_f32_e32 v56, 0x4b800000, v52
	v_cmp_gt_f32_e32 vcc, s55, v52
	s_nop 1
	v_cndmask_b32_e32 v52, v52, v56, vcc
	v_rsq_f32_e32 v52, v52
	s_nop 0
	v_mul_f32_e32 v56, 0x45800000, v52
	v_cndmask_b32_e32 v52, v52, v56, vcc
	v_mul_f32_e32 v52, v53, v52
	ds_write_b32 v3, v52 offset:62224
	ds_read_b128 v[56:59], v71
	ds_read_b128 v[88:91], v71 offset:16
	v_add_u32_e32 v71, 0x1ef0, v3
	s_waitcnt lgkmcnt(0)
	v_pk_add_f32 v[52:53], v[58:59], v[90:91]
	v_pk_add_f32 v[56:57], v[56:57], v[88:89]
	v_mov_b64_e32 v[90:91], v[6:7]
	v_pk_mov_b32 v[58:59], v[56:57], v[52:53] op_sel:[1,0]
	v_mov_b32_e32 v57, v53
	v_pk_add_f32 v[52:53], v[58:59], v[56:57]
	v_lshl_add_u32 v56, v55, 5, s54
	v_add_f32_e32 v52, v52, v53
	v_fmamk_f32 v52, v52, 0x3c000000, v151
	v_mul_f32_e32 v53, 0x4b800000, v52
	v_cmp_gt_f32_e32 vcc, s55, v52
	v_mov_b64_e32 v[88:89], v[4:5]
	s_nop 0
	v_cndmask_b32_e32 v52, v52, v53, vcc
	v_rsq_f32_e32 v52, v52
	s_nop 0
	v_mul_f32_e32 v53, 0x45800000, v52
	v_cndmask_b32_e32 v52, v52, v53, vcc
	v_mul_f32_e32 v52, v54, v52
	ds_write_b32 v3, v52 offset:62752
	ds_read_b128 v[52:55], v56
	ds_read_b128 v[56:59], v56 offset:16
	v_add_u32_e32 v3, 0x3ff0, v3
	s_waitcnt lgkmcnt(0)
	v_pk_add_f32 v[54:55], v[54:55], v[58:59]
	v_pk_add_f32 v[52:53], v[52:53], v[56:57]
	s_nop 0
	v_pk_mov_b32 v[56:57], v[52:53], v[54:55] op_sel:[1,0]
	v_mov_b32_e32 v53, v55
	v_pk_add_f32 v[52:53], v[56:57], v[52:53]
	v_lshl_add_u32 v56, v79, 5, s54
	v_add_f32_e32 v52, v52, v53
	v_fmamk_f32 v52, v52, 0x3c000000, v151
	v_mul_f32_e32 v53, 0x4b800000, v52
	v_cmp_gt_f32_e32 vcc, s55, v52
	s_nop 1
	v_cndmask_b32_e32 v52, v52, v53, vcc
	v_rsq_f32_e32 v52, v52
	s_nop 0
	v_mul_f32_e32 v53, 0x45800000, v52
	v_cndmask_b32_e32 v52, v52, v53, vcc
	v_mul_f32_e32 v48, v48, v52
	ds_write_b32 v71, v48 offset:61696
	ds_read_b128 v[52:55], v56
	ds_read_b128 v[56:59], v56 offset:16
	s_waitcnt lgkmcnt(0)
	v_pk_add_f32 v[54:55], v[54:55], v[58:59]
	v_pk_add_f32 v[52:53], v[52:53], v[56:57]
	s_nop 0
	v_pk_mov_b32 v[56:57], v[52:53], v[54:55] op_sel:[1,0]
	v_mov_b32_e32 v53, v55
	v_pk_add_f32 v[52:53], v[56:57], v[52:53]
	v_lshl_add_u32 v56, v72, 5, s54
	v_add_f32_e32 v48, v52, v53
	v_fmamk_f32 v48, v48, 0x3c000000, v151
	v_mul_f32_e32 v52, 0x4b800000, v48
	v_cmp_gt_f32_e32 vcc, s55, v48
	v_lshlrev_b32_e32 v72, 16, v65
	v_and_b32_e32 v65, 0xffff0000, v65
	v_cndmask_b32_e32 v48, v48, v52, vcc
	v_rsq_f32_e32 v48, v48
	s_nop 0
	v_mul_f32_e32 v52, 0x45800000, v48
	v_cndmask_b32_e32 v48, v48, v52, vcc
	v_mul_f32_e32 v48, v73, v48
	ds_write_b32 v71, v48 offset:62224
	ds_read_b128 v[52:55], v56
	ds_read_b128 v[56:59], v56 offset:16
	v_lshlrev_b32_e32 v73, 16, v66
	s_waitcnt lgkmcnt(0)
	v_pk_add_f32 v[54:55], v[54:55], v[58:59]
	v_pk_add_f32 v[52:53], v[52:53], v[56:57]
	s_nop 0
	v_pk_mov_b32 v[56:57], v[52:53], v[54:55] op_sel:[1,0]
	v_mov_b32_e32 v53, v55
	v_pk_add_f32 v[52:53], v[56:57], v[52:53]
	v_lshl_add_u32 v56, v74, 5, s54
	v_add_f32_e32 v48, v52, v53
	v_fmamk_f32 v48, v48, 0x3c000000, v151
	v_mul_f32_e32 v52, 0x4b800000, v48
	v_cmp_gt_f32_e32 vcc, s55, v48
	v_and_b32_e32 v74, 0xffff0000, v66
	v_lshl_add_u64 v[66:67], s[0:1], 0, v[82:83]
	v_cndmask_b32_e32 v48, v48, v52, vcc
	v_rsq_f32_e32 v48, v48
	s_nop 0
	v_mul_f32_e32 v52, 0x45800000, v48
	v_cndmask_b32_e32 v48, v48, v52, vcc
	v_mul_f32_e32 v48, v49, v48
	ds_write_b32 v71, v48 offset:62752
	ds_read_b128 v[52:55], v56
	ds_read_b128 v[56:59], v56 offset:16
	s_waitcnt lgkmcnt(0)
	v_pk_add_f32 v[48:49], v[54:55], v[58:59]
	v_pk_add_f32 v[52:53], v[52:53], v[56:57]
	s_nop 0
	v_pk_mov_b32 v[54:55], v[52:53], v[48:49] op_sel:[1,0]
	v_mov_b32_e32 v53, v49
	v_pk_add_f32 v[48:49], v[54:55], v[52:53]
	s_nop 0
	v_add_f32_e32 v48, v48, v49
	v_fmamk_f32 v48, v48, 0x3c000000, v151
	v_mul_f32_e32 v49, 0x4b800000, v48
	v_cmp_gt_f32_e32 vcc, s55, v48
	s_nop 1
	v_cndmask_b32_e32 v48, v48, v49, vcc
	v_rsq_f32_e32 v48, v48
	v_add_u32_e32 v49, s54, v70
	v_lshlrev_b32_e32 v70, 2, v156
	v_mul_f32_e32 v52, 0x45800000, v48
	v_cndmask_b32_e32 v48, v48, v52, vcc
	v_mul_f32_e32 v48, v50, v48
	ds_write_b32 v71, v48 offset:63280
	ds_read_b128 v[52:55], v49
	ds_read_b128 v[56:59], v49 offset:16
	v_and_b32_e32 v71, 0xffff0000, v64
	s_waitcnt lgkmcnt(0)
	v_pk_add_f32 v[48:49], v[54:55], v[58:59]
	v_pk_add_f32 v[52:53], v[52:53], v[56:57]
	v_lshlrev_b64 v[58:59], 11, v[84:85]
	v_pk_mov_b32 v[54:55], v[52:53], v[48:49] op_sel:[1,0]
	v_mov_b32_e32 v53, v49
	v_pk_add_f32 v[48:49], v[54:55], v[52:53]
	v_add_u32_e32 v52, s54, v69
	v_add_f32_e32 v48, v48, v49
	v_fmamk_f32 v48, v48, 0x3c000000, v151
	v_mul_f32_e32 v49, 0x4b800000, v48
	v_cmp_gt_f32_e32 vcc, s55, v48
	s_nop 1
	v_cndmask_b32_e32 v48, v48, v49, vcc
	v_rsq_f32_e32 v48, v48
	s_nop 0
	v_mul_f32_e32 v49, 0x45800000, v48
	v_cndmask_b32_e32 v48, v48, v49, vcc
	v_mul_f32_e32 v48, v51, v48
	ds_write_b32 v3, v48 offset:61696
	ds_read_b128 v[48:51], v52
	ds_read_b128 v[52:55], v52 offset:16
	s_waitcnt lgkmcnt(0)
	v_pk_add_f32 v[50:51], v[50:51], v[54:55]
	v_pk_add_f32 v[48:49], v[48:49], v[52:53]
	s_nop 0
	v_pk_mov_b32 v[52:53], v[48:49], v[50:51] op_sel:[1,0]
	v_mov_b32_e32 v49, v51
	v_pk_add_f32 v[48:49], v[52:53], v[48:49]
	s_nop 0
	v_add_f32_e32 v48, v48, v49
	v_fmamk_f32 v48, v48, 0x3c000000, v151
	v_mul_f32_e32 v49, 0x4b800000, v48
	v_cmp_gt_f32_e32 vcc, s55, v48
	s_nop 1
	v_cndmask_b32_e32 v48, v48, v49, vcc
	v_rsq_f32_e32 v48, v48
	s_nop 0
	v_mul_f32_e32 v49, 0x45800000, v48
	v_cndmask_b32_e32 v48, v48, v49, vcc
	v_mul_f32_e32 v48, v68, v48
	ds_write_b32 v3, v48 offset:62224
	ds_read_b128 v[48:51], v47
	ds_read_b128 v[52:55], v47 offset:16
	v_lshl_add_u64 v[68:69], v[66:67], 0, v[58:59]
	s_waitcnt lgkmcnt(0)
	v_pk_add_f32 v[50:51], v[50:51], v[54:55]
	v_pk_add_f32 v[48:49], v[48:49], v[52:53]
	s_nop 0
	v_pk_mov_b32 v[52:53], v[48:49], v[50:51] op_sel:[1,0]
	v_mov_b32_e32 v49, v51
	v_pk_add_f32 v[48:49], v[52:53], v[48:49]
	v_add_u32_e32 v50, s54, v46
	v_add_f32_e32 v47, v48, v49
	v_fmamk_f32 v47, v47, 0x3c000000, v151
	v_mul_f32_e32 v48, 0x4b800000, v47
	v_cmp_gt_f32_e32 vcc, s55, v47
	s_nop 1
	v_cndmask_b32_e32 v47, v47, v48, vcc
	v_rsq_f32_e32 v47, v47
	s_nop 0
	v_mul_f32_e32 v46, 0x45800000, v47
	v_cndmask_b32_e32 v46, v47, v46, vcc
	v_mul_f32_e32 v45, v45, v46
	ds_write_b32 v3, v45 offset:62752
	ds_read_b128 v[46:49], v50
	ds_read_b128 v[50:53], v50 offset:16
	s_waitcnt lgkmcnt(0)
	v_pk_add_f32 v[48:49], v[48:49], v[52:53]
	v_pk_add_f32 v[46:47], v[46:47], v[50:51]
	s_nop 0
	v_pk_mov_b32 v[50:51], v[46:47], v[48:49] op_sel:[1,0]
	v_mov_b32_e32 v47, v49
	v_pk_add_f32 v[46:47], v[50:51], v[46:47]
	s_nop 0
	v_add_f32_e32 v45, v46, v47
	v_fmamk_f32 v45, v45, 0x3c000000, v151
	v_mul_f32_e32 v46, 0x4b800000, v45
	v_cmp_gt_f32_e32 vcc, s55, v45
	s_nop 1
	v_cndmask_b32_e32 v45, v45, v46, vcc
	v_rsq_f32_e32 v45, v45
	s_nop 0
	v_mul_f32_e32 v46, 0x45800000, v45
	v_cndmask_b32_e32 v45, v45, v46, vcc
	v_mul_f32_e32 v44, v44, v45
	ds_write_b32 v3, v44 offset:63280
	s_waitcnt lgkmcnt(0)
	s_barrier
	s_waitcnt vmcnt(0)
	v_mov_b32_e32 v44, v200
	v_mov_b32_e32 v45, v201
	v_mov_b32_e32 v46, v202
	v_mov_b32_e32 v47, v203
	v_mov_b32_e32 v48, v204
	v_mov_b32_e32 v49, v205
	v_mov_b32_e32 v50, v206
	v_mov_b32_e32 v51, v207
	v_lshlrev_b32_e32 v3, 16, v64
	v_add_u32_e32 v64, 0, v70
	v_mad_u64_u32 v[56:57], s[12:13], v86, s95, v[64:65]
	ds_read_b128 v[52:55], v56 offset:53248
	ds_read_b128 v[56:59], v56 offset:53264
	v_mov_b64_e32 v[86:87], v[42:43]
	v_mov_b64_e32 v[84:85], v[40:41]
	s_andn2_b64 vcc, exec, s[24:25]
	s_waitcnt vmcnt(1) lgkmcnt(1)
	v_mul_f32_e32 v44, v52, v44
	v_mul_f32_e32 v45, v53, v45
	v_mul_f32_e32 v46, v54, v46
	v_mul_f32_e32 v47, v55, v47
	s_waitcnt vmcnt(0) lgkmcnt(0)
	v_mul_f32_e32 v48, v56, v48
	v_mul_f32_e32 v49, v57, v49
	v_mul_f32_e32 v50, v58, v50
	v_mul_f32_e32 v51, v59, v51
	v_mul_f32_e32 v3, v44, v3
	v_mul_f32_e32 v44, v45, v71
	v_mul_f32_e32 v45, v46, v72
	v_mul_f32_e32 v46, v47, v65
	v_mul_f32_e32 v47, v48, v73
	v_mul_f32_e32 v48, v49, v74
	v_mul_f32_e32 v49, v50, v75
	v_mul_f32_e32 v50, v51, v76
	v_cvt_pk_bf16_f32 v44, v3, v44
	v_cvt_pk_bf16_f32 v45, v45, v46
	v_cvt_pk_bf16_f32 v46, v47, v48
	v_cvt_pk_bf16_f32 v47, v49, v50
	global_store_dwordx4 v[68:69], v[44:47], off
	s_nop 1
	v_mov_b32_e32 v44, v200
	v_mov_b32_e32 v45, v201
	v_mov_b32_e32 v46, v202
	v_mov_b32_e32 v47, v203
	s_nop 0
	v_mov_b32_e32 v48, v204
	v_mov_b32_e32 v49, v205
	v_mov_b32_e32 v50, v206
	v_mov_b32_e32 v51, v207
	v_lshlrev_b32_e32 v65, 16, v60
	v_lshlrev_b64 v[52:53], 11, v[80:81]
	v_mad_u64_u32 v[2:3], s[0:1], v2, s95, v[64:65]
	v_lshl_add_u64 v[60:61], v[66:67], 0, v[52:53]
	ds_read_b128 v[52:55], v2 offset:53248
	ds_read_b128 v[56:59], v2 offset:53264
	v_mov_b64_e32 v[82:83], v[38:39]
	v_mov_b64_e32 v[74:75], v[34:35]
	v_mov_b64_e32 v[78:79], v[30:31]
	v_mov_b64_e32 v[70:71], v[26:27]
	v_mov_b64_e32 v[80:81], v[36:37]
	v_mov_b64_e32 v[72:73], v[32:33]
	v_mov_b64_e32 v[76:77], v[28:29]
	v_mov_b64_e32 v[68:69], v[24:25]
	s_waitcnt lgkmcnt(1)
	v_mul_f32_e32 v2, v52, v44
	v_mul_f32_e32 v3, v53, v45
	v_mul_f32_e32 v44, v54, v46
	v_mul_f32_e32 v45, v55, v47
	s_waitcnt lgkmcnt(0)
	v_mul_f32_e32 v46, v56, v48
	v_mul_f32_e32 v47, v57, v49
	v_mul_f32_e32 v48, v58, v50
	v_mul_f32_e32 v49, v59, v51
	v_mul_f32_e32 v45, v45, v113
	v_mul_f32_e32 v46, v46, v114
	v_mul_f32_e32 v47, v47, v62
	v_mul_f32_e32 v2, v2, v65
	v_mul_f32_e32 v3, v3, v108
	v_mul_f32_e32 v50, v44, v109
	v_mul_f32_e32 v48, v48, v115
	v_mul_f32_e32 v49, v49, v63
	v_cvt_pk_bf16_f32 v44, v2, v3
	v_cvt_pk_bf16_f32 v45, v50, v45
	v_cvt_pk_bf16_f32 v46, v46, v47
	v_cvt_pk_bf16_f32 v47, v48, v49
	global_store_dwordx4 v[60:61], v[44:47], off
	s_cbranch_vccz .LBB0_743
